# v13 + counted waits at GEMM tile boundary: epilogue stores drain under the peeled first K-iteration (vmcnt(16) on its first two waits), full drain only after the job prologue
# baseline (speedup 1.0000x reference)
.LBB0_164:
	v_lshlrev_b32_e32 v15, 2, v229
	s_add_i32 m0, s70, 0x18000
	v_lshl_add_u64 v[2:3], v[2:3], 0, s[20:21]
	s_and_b32 s66, s7, 3
	v_lshl_or_b32 v14, v229, 6, v230
	s_lshl_b32 s7, s8, 13
	v_and_b32_e32 v15, 32, v15
	s_waitcnt vmcnt(2)
	s_barrier
	global_load_lds_dwordx4 v[2:3], off
	v_lshl_add_u64 v[2:3], v[4:5], 0, s[20:21]
	s_add_i32 m0, s70, 0x1a000
	s_add_i32 s67, s70, 0x8000
	v_bitop3_b32 v14, v14, s7, v15 bitop3:0xde
	global_load_lds_dwordx4 v[2:3], off
	v_lshl_add_u64 v[2:3], v[10:11], 0, s[20:21]
	s_mov_b32 m0, s67
	s_add_i32 s7, s70, 0xa000
	global_load_lds_dwordx4 v[2:3], off
	v_lshl_add_u64 v[2:3], v[12:13], 0, s[20:21]
	s_mov_b32 m0, s7
	s_add_i32 s18, s61, -2
	global_load_lds_dwordx4 v[2:3], off
	s_add_i32 m0, s70, 0x1c000
	v_lshl_add_u64 v[2:3], v[6:7], 0, s[20:21]
	global_load_lds_dwordx4 v[2:3], off
	v_lshl_add_u64 v[2:3], v[8:9], 0, s[20:21]
	s_add_i32 m0, s70, 0x1e000
	s_cmpk_lt_u32 s6, 0x100
	global_load_lds_dwordx4 v[2:3], off
	s_cselect_b64 s[84:85], -1, 0
	s_lshr_b32 s94, s74, 3
	v_lshl_or_b32 v233, s8, 6, v229
	s_ashr_i32 s19, s55, 31
	s_and_b32 s6, s74, 7
	s_add_i32 s8, s94, 1
	s_lshl_b32 s9, s12, 2
	s_cmp_lg_u64 s[72:73], 0
	s_cselect_b64 s[86:87], -1, 0
	s_cmp_lg_u64 s[48:49], 0
	s_cselect_b64 s[22:23], -1, 0
	v_lshlrev_b32_e32 v2, 2, v170
	v_mov_b32_e32 v3, v1
	s_abs_i32 s13, s9
	v_lshl_add_u64 v[178:179], s[0:1], 0, v[2:3]
	v_cvt_f32_u32_e32 v2, s13
	s_sub_i32 s0, 0, s13
	s_waitcnt vmcnt(6)
	v_lshl_or_b32 v234, s66, 12, v231
	v_rcp_iflag_f32_e32 v2, v2
	v_lshl_or_b32 v235, s66, 4, v232
	s_mov_b32 s75, s93
	v_lshl_or_b32 v236, s66, 5, v170
	v_mul_f32_e32 v2, 0x4f7ffffe, v2
	v_cvt_u32_f32_e32 v2, v2
	s_bfe_i32 s12, s12, 0x1001d
	s_mov_b32 s36, 0
	v_lshl_add_u64 v[180:181], s[80:81], 0, v[172:173]
	v_readfirstlane_b32 s1, v2
	v_cvt_f32_u32_e32 v2, s62
	s_mul_i32 s0, s0, s1
	s_mul_hi_u32 s0, s1, s0
	s_add_i32 s37, s1, s0
	v_rcp_iflag_f32_e32 v2, v2
	s_sub_i32 s0, 0, s62
	v_lshl_add_u64 v[182:183], s[80:81], 0, v[174:175]
	v_add_u32_e32 v237, 0, v14
	v_mul_f32_e32 v2, 0x4f7ffffe, v2
	v_cvt_u32_f32_e32 v2, v2
	s_barrier
	v_readfirstlane_b32 s1, v2
	s_mul_i32 s0, s0, s1
	s_mul_hi_u32 s0, s1, s0
	s_add_i32 s96, s1, s0
	s_waitcnt vmcnt(0)
	s_branch .LBB0_167

.Lk_peel:
	s_add_i32 s44, s14, 2
	s_add_u32 s45, s0, 0x80
	s_addc_u32 s15, s1, 0
	s_add_i32 s57, 0, 0x10000
	s_cmp_eq_u32 s18, s14
	s_cselect_b32 s15, s89, s15
	s_cselect_b32 s14, s88, s45
	s_cselect_b32 vcc_hi, s11, s43
	s_cselect_b32 vcc_lo, s10, s42
	s_add_i32 s45, 0, 0x14000
	s_waitcnt lgkmcnt(0)
	ds_read_b128 v[130:133], v248
	ds_read_b128 v[134:137], v248 offset:1024
	ds_read_b128 v[138:141], v248 offset:2048
	ds_read_b128 v[142:145], v248 offset:3072
	ds_read_b128 v[146:149], v248 offset:16384
	ds_read_b128 v[150:153], v248 offset:17408
	ds_read_b128 v[154:157], v248 offset:18432
	ds_read_b128 v[158:161], v248 offset:19456
	s_add_i32 m0, s70, 0xc000
	ds_read_b128 v[162:165], v237
	ds_read_b128 v[166:169], v237 offset:1024
	ds_read_b128 v[184:187], v237 offset:2048
	ds_read_b128 v[188:191], v237 offset:3072
	ds_read_b128 v[192:195], v237 offset:4096
	ds_read_b128 v[196:199], v237 offset:5120
	ds_read_b128 v[200:203], v237 offset:6144
	ds_read_b128 v[214:217], v237 offset:7168
	global_load_lds_dwordx4 v180, s[0:1]
	s_add_i32 m0, s70, 0xe000
	s_nop 0
	global_load_lds_dwordx4 v182, s[0:1]
	s_waitcnt vmcnt(16)
	s_waitcnt lgkmcnt(0)
	s_barrier
	s_setprio 1
	s_waitcnt lgkmcnt(0)
	v_mfma_f32_16x16x32_bf16 v[122:125], v[130:133], v[162:165], 0
	v_mfma_f32_16x16x32_bf16 v[126:129], v[138:141], v[162:165], 0
	v_mfma_f32_16x16x32_bf16 v[106:109], v[130:133], v[184:187], 0
	v_mfma_f32_16x16x32_bf16 v[110:113], v[138:141], v[184:187], 0
	v_mfma_f32_16x16x32_bf16 v[90:93], v[130:133], v[192:195], 0
	v_mfma_f32_16x16x32_bf16 v[94:97], v[138:141], v[192:195], 0
	v_mfma_f32_16x16x32_bf16 v[74:77], v[130:133], v[200:203], 0
	v_mfma_f32_16x16x32_bf16 v[78:81], v[138:141], v[200:203], 0
	v_mfma_f32_16x16x32_bf16 v[122:125], v[134:137], v[166:169], v[122:125]
	v_mfma_f32_16x16x32_bf16 v[126:129], v[142:145], v[166:169], v[126:129]
	v_mfma_f32_16x16x32_bf16 v[106:109], v[134:137], v[188:191], v[106:109]
	v_mfma_f32_16x16x32_bf16 v[110:113], v[142:145], v[188:191], v[110:113]
	v_mfma_f32_16x16x32_bf16 v[90:93], v[134:137], v[196:199], v[90:93]
	v_mfma_f32_16x16x32_bf16 v[94:97], v[142:145], v[196:199], v[94:97]
	v_mfma_f32_16x16x32_bf16 v[74:77], v[134:137], v[214:217], v[74:77]
	v_mfma_f32_16x16x32_bf16 v[78:81], v[142:145], v[214:217], v[78:81]
	v_mfma_f32_16x16x32_bf16 v[114:117], v[146:149], v[162:165], 0
	v_mfma_f32_16x16x32_bf16 v[118:121], v[154:157], v[162:165], 0
	v_mfma_f32_16x16x32_bf16 v[98:101], v[146:149], v[184:187], 0
	v_mfma_f32_16x16x32_bf16 v[102:105], v[154:157], v[184:187], 0
	v_mfma_f32_16x16x32_bf16 v[82:85], v[146:149], v[192:195], 0
	v_mfma_f32_16x16x32_bf16 v[86:89], v[154:157], v[192:195], 0
	v_mfma_f32_16x16x32_bf16 v[66:69], v[146:149], v[200:203], 0
	v_mfma_f32_16x16x32_bf16 v[70:73], v[154:157], v[200:203], 0
	v_mfma_f32_16x16x32_bf16 v[114:117], v[150:153], v[166:169], v[114:117]
	v_mfma_f32_16x16x32_bf16 v[118:121], v[158:161], v[166:169], v[118:121]
	v_mfma_f32_16x16x32_bf16 v[98:101], v[150:153], v[188:191], v[98:101]
	v_mfma_f32_16x16x32_bf16 v[102:105], v[158:161], v[188:191], v[102:105]
	v_mfma_f32_16x16x32_bf16 v[82:85], v[150:153], v[196:199], v[82:85]
	v_mfma_f32_16x16x32_bf16 v[86:89], v[158:161], v[196:199], v[86:89]
	v_mfma_f32_16x16x32_bf16 v[66:69], v[150:153], v[214:217], v[66:69]
	v_mfma_f32_16x16x32_bf16 v[70:73], v[158:161], v[214:217], v[70:73]
	s_setprio 0
	s_barrier
	s_add_i32 s57, s57, s59
	s_mov_b32 m0, s57
	ds_read_b128 v[162:165], v237 offset:16384
	ds_read_b128 v[166:169], v237 offset:17408
	ds_read_b128 v[184:187], v237 offset:18432
	ds_read_b128 v[188:191], v237 offset:19456
	ds_read_b128 v[192:195], v237 offset:20480
	ds_read_b128 v[196:199], v237 offset:21504
	ds_read_b128 v[200:203], v237 offset:22528
	ds_read_b128 v[214:217], v237 offset:23552
	global_load_lds_dwordx4 v0, vcc
	s_add_i32 m0, s57, 0x2000
	s_add_i32 s45, s45, s59
	global_load_lds_dwordx4 v176, vcc
	s_mov_b32 m0, s45
	s_nop 0
	global_load_lds_dwordx4 v242, vcc
	s_add_i32 m0, s45, 0x2000
	s_nop 0
	global_load_lds_dwordx4 v249, vcc
	s_mov_b32 m0, s70
	s_nop 0
	global_load_lds_dwordx4 v172, s[14:15]
	s_mov_b32 m0, s4
	s_nop 0
	global_load_lds_dwordx4 v174, s[14:15]
	s_waitcnt vmcnt(16)
	s_waitcnt lgkmcnt(0)
	s_barrier
	s_setprio 1
	s_waitcnt lgkmcnt(0)
	v_mfma_f32_16x16x32_bf16 v[58:61], v[130:133], v[162:165], 0
	v_mfma_f32_16x16x32_bf16 v[62:65], v[138:141], v[162:165], 0
	v_mfma_f32_16x16x32_bf16 v[42:45], v[130:133], v[184:187], 0
	v_mfma_f32_16x16x32_bf16 v[46:49], v[138:141], v[184:187], 0
	v_mfma_f32_16x16x32_bf16 v[26:29], v[130:133], v[192:195], 0
	v_mfma_f32_16x16x32_bf16 v[30:33], v[138:141], v[192:195], 0
	v_mfma_f32_16x16x32_bf16 v[10:13], v[130:133], v[200:203], 0
	v_mfma_f32_16x16x32_bf16 v[14:17], v[138:141], v[200:203], 0
	v_mfma_f32_16x16x32_bf16 v[58:61], v[134:137], v[166:169], v[58:61]
	v_mfma_f32_16x16x32_bf16 v[62:65], v[142:145], v[166:169], v[62:65]
	v_mfma_f32_16x16x32_bf16 v[42:45], v[134:137], v[188:191], v[42:45]
	v_mfma_f32_16x16x32_bf16 v[46:49], v[142:145], v[188:191], v[46:49]
	v_mfma_f32_16x16x32_bf16 v[26:29], v[134:137], v[196:199], v[26:29]
	v_mfma_f32_16x16x32_bf16 v[30:33], v[142:145], v[196:199], v[30:33]
	v_mfma_f32_16x16x32_bf16 v[10:13], v[134:137], v[214:217], v[10:13]
	v_mfma_f32_16x16x32_bf16 v[14:17], v[142:145], v[214:217], v[14:17]
	v_mfma_f32_16x16x32_bf16 v[50:53], v[146:149], v[162:165], 0
	v_mfma_f32_16x16x32_bf16 v[54:57], v[154:157], v[162:165], 0
	v_mfma_f32_16x16x32_bf16 v[34:37], v[146:149], v[184:187], 0
	v_mfma_f32_16x16x32_bf16 v[38:41], v[154:157], v[184:187], 0
	v_mfma_f32_16x16x32_bf16 v[18:21], v[146:149], v[192:195], 0
	v_mfma_f32_16x16x32_bf16 v[22:25], v[154:157], v[192:195], 0
	v_mfma_f32_16x16x32_bf16 v[6:9], v[146:149], v[200:203], 0
	v_mfma_f32_16x16x32_bf16 v[2:5], v[154:157], v[200:203], 0
	v_mfma_f32_16x16x32_bf16 v[50:53], v[150:153], v[166:169], v[50:53]
	v_mfma_f32_16x16x32_bf16 v[54:57], v[158:161], v[166:169], v[54:57]
	v_mfma_f32_16x16x32_bf16 v[34:37], v[150:153], v[188:191], v[34:37]
	v_mfma_f32_16x16x32_bf16 v[38:41], v[158:161], v[188:191], v[38:41]
	v_mfma_f32_16x16x32_bf16 v[18:21], v[150:153], v[196:199], v[18:21]
	v_mfma_f32_16x16x32_bf16 v[22:25], v[158:161], v[196:199], v[22:25]
	v_mfma_f32_16x16x32_bf16 v[6:9], v[150:153], v[214:217], v[6:9]
	v_mfma_f32_16x16x32_bf16 v[2:5], v[158:161], v[214:217], v[2:5]
	s_setprio 0
	s_barrier
	s_add_i32 s45, 0, 0x18000
	s_add_i32 s57, 0, 0x1c000
	ds_read_b128 v[130:133], v248 offset:32768
	ds_read_b128 v[134:137], v248 offset:33792
	ds_read_b128 v[138:141], v248 offset:34816
	ds_read_b128 v[142:145], v248 offset:35840
	ds_read_b128 v[146:149], v248 offset:49152
	ds_read_b128 v[150:153], v248 offset:50176
	ds_read_b128 v[154:157], v248 offset:51200
	ds_read_b128 v[158:161], v248 offset:52224
	s_mov_b32 m0, s63
	ds_read_b128 v[162:165], v237 offset:32768
	ds_read_b128 v[166:169], v237 offset:33792
	ds_read_b128 v[184:187], v237 offset:34816
	ds_read_b128 v[188:191], v237 offset:35840
	ds_read_b128 v[192:195], v237 offset:36864
	ds_read_b128 v[196:199], v237 offset:37888
	ds_read_b128 v[200:203], v237 offset:38912
	ds_read_b128 v[214:217], v237 offset:39936
	global_load_lds_dwordx4 v180, s[14:15]
	s_mov_b32 m0, s68
	s_nop 0
	global_load_lds_dwordx4 v182, s[14:15]
	s_waitcnt vmcnt(8)
	s_waitcnt lgkmcnt(0)
	s_barrier
	s_setprio 1
	s_waitcnt lgkmcnt(0)
	v_mfma_f32_16x16x32_bf16 v[122:125], v[130:133], v[162:165], v[122:125]
	v_mfma_f32_16x16x32_bf16 v[126:129], v[138:141], v[162:165], v[126:129]
	v_mfma_f32_16x16x32_bf16 v[106:109], v[130:133], v[184:187], v[106:109]
	v_mfma_f32_16x16x32_bf16 v[110:113], v[138:141], v[184:187], v[110:113]
	v_mfma_f32_16x16x32_bf16 v[90:93], v[130:133], v[192:195], v[90:93]
	v_mfma_f32_16x16x32_bf16 v[94:97], v[138:141], v[192:195], v[94:97]
	v_mfma_f32_16x16x32_bf16 v[74:77], v[130:133], v[200:203], v[74:77]
	v_mfma_f32_16x16x32_bf16 v[78:81], v[138:141], v[200:203], v[78:81]
	v_mfma_f32_16x16x32_bf16 v[122:125], v[134:137], v[166:169], v[122:125]
	v_mfma_f32_16x16x32_bf16 v[126:129], v[142:145], v[166:169], v[126:129]
	v_mfma_f32_16x16x32_bf16 v[106:109], v[134:137], v[188:191], v[106:109]
	v_mfma_f32_16x16x32_bf16 v[110:113], v[142:145], v[188:191], v[110:113]
	v_mfma_f32_16x16x32_bf16 v[90:93], v[134:137], v[196:199], v[90:93]
	v_mfma_f32_16x16x32_bf16 v[94:97], v[142:145], v[196:199], v[94:97]
	v_mfma_f32_16x16x32_bf16 v[74:77], v[134:137], v[214:217], v[74:77]
	v_mfma_f32_16x16x32_bf16 v[78:81], v[142:145], v[214:217], v[78:81]
	v_mfma_f32_16x16x32_bf16 v[114:117], v[146:149], v[162:165], v[114:117]
	v_mfma_f32_16x16x32_bf16 v[118:121], v[154:157], v[162:165], v[118:121]
	v_mfma_f32_16x16x32_bf16 v[98:101], v[146:149], v[184:187], v[98:101]
	v_mfma_f32_16x16x32_bf16 v[102:105], v[154:157], v[184:187], v[102:105]
	v_mfma_f32_16x16x32_bf16 v[82:85], v[146:149], v[192:195], v[82:85]
	v_mfma_f32_16x16x32_bf16 v[86:89], v[154:157], v[192:195], v[86:89]
	v_mfma_f32_16x16x32_bf16 v[66:69], v[146:149], v[200:203], v[66:69]
	v_mfma_f32_16x16x32_bf16 v[70:73], v[154:157], v[200:203], v[70:73]
	v_mfma_f32_16x16x32_bf16 v[114:117], v[150:153], v[166:169], v[114:117]
	v_mfma_f32_16x16x32_bf16 v[118:121], v[158:161], v[166:169], v[118:121]
	v_mfma_f32_16x16x32_bf16 v[98:101], v[150:153], v[188:191], v[98:101]
	v_mfma_f32_16x16x32_bf16 v[102:105], v[158:161], v[188:191], v[102:105]
	v_mfma_f32_16x16x32_bf16 v[82:85], v[150:153], v[196:199], v[82:85]
	v_mfma_f32_16x16x32_bf16 v[86:89], v[158:161], v[196:199], v[86:89]
	v_mfma_f32_16x16x32_bf16 v[66:69], v[150:153], v[214:217], v[66:69]
	v_mfma_f32_16x16x32_bf16 v[70:73], v[158:161], v[214:217], v[70:73]
	s_setprio 0
	s_barrier
	s_add_i32 m0, s45, s59
	ds_read_b128 v[162:165], v237 offset:49152
	ds_read_b128 v[166:169], v237 offset:50176
	ds_read_b128 v[184:187], v237 offset:51200
	ds_read_b128 v[188:191], v237 offset:52224
	ds_read_b128 v[192:195], v237 offset:53248
	ds_read_b128 v[196:199], v237 offset:54272
	ds_read_b128 v[200:203], v237 offset:55296
	ds_read_b128 v[214:217], v237 offset:56320
	global_load_lds_dwordx4 v204, vcc
	s_add_i32 m0, m0, 0x2000
	s_nop 0
	global_load_lds_dwordx4 v205, vcc
	s_add_i32 m0, s57, s59
	s_nop 0
	global_load_lds_dwordx4 v218, vcc
	s_add_i32 m0, m0, 0x2000
	s_nop 0
	global_load_lds_dwordx4 v219, vcc
	s_mov_b32 m0, s67
	s_nop 0
	global_load_lds_dwordx4 v220, s[14:15]
	s_mov_b32 m0, s7
	s_nop 0
	global_load_lds_dwordx4 v221, s[14:15]
	s_waitcnt vmcnt(8)
	s_waitcnt lgkmcnt(0)
	s_barrier
	s_setprio 1
	s_waitcnt lgkmcnt(0)
	v_mfma_f32_16x16x32_bf16 v[58:61], v[130:133], v[162:165], v[58:61]
	v_mfma_f32_16x16x32_bf16 v[62:65], v[138:141], v[162:165], v[62:65]
	v_mfma_f32_16x16x32_bf16 v[42:45], v[130:133], v[184:187], v[42:45]
	v_mfma_f32_16x16x32_bf16 v[46:49], v[138:141], v[184:187], v[46:49]
	v_mfma_f32_16x16x32_bf16 v[26:29], v[130:133], v[192:195], v[26:29]
	v_mfma_f32_16x16x32_bf16 v[30:33], v[138:141], v[192:195], v[30:33]
	v_mfma_f32_16x16x32_bf16 v[10:13], v[130:133], v[200:203], v[10:13]
	v_mfma_f32_16x16x32_bf16 v[14:17], v[138:141], v[200:203], v[14:17]
	v_mfma_f32_16x16x32_bf16 v[58:61], v[134:137], v[166:169], v[58:61]
	v_mfma_f32_16x16x32_bf16 v[62:65], v[142:145], v[166:169], v[62:65]
	v_mfma_f32_16x16x32_bf16 v[42:45], v[134:137], v[188:191], v[42:45]
	v_mfma_f32_16x16x32_bf16 v[46:49], v[142:145], v[188:191], v[46:49]
	v_mfma_f32_16x16x32_bf16 v[26:29], v[134:137], v[196:199], v[26:29]
	v_mfma_f32_16x16x32_bf16 v[30:33], v[142:145], v[196:199], v[30:33]
	v_mfma_f32_16x16x32_bf16 v[10:13], v[134:137], v[214:217], v[10:13]
	v_mfma_f32_16x16x32_bf16 v[14:17], v[142:145], v[214:217], v[14:17]
	v_mfma_f32_16x16x32_bf16 v[50:53], v[146:149], v[162:165], v[50:53]
	v_mfma_f32_16x16x32_bf16 v[54:57], v[154:157], v[162:165], v[54:57]
	v_mfma_f32_16x16x32_bf16 v[34:37], v[146:149], v[184:187], v[34:37]
	v_mfma_f32_16x16x32_bf16 v[38:41], v[154:157], v[184:187], v[38:41]
	v_mfma_f32_16x16x32_bf16 v[18:21], v[146:149], v[192:195], v[18:21]
	v_mfma_f32_16x16x32_bf16 v[22:25], v[154:157], v[192:195], v[22:25]
	v_mfma_f32_16x16x32_bf16 v[6:9], v[146:149], v[200:203], v[6:9]
	v_mfma_f32_16x16x32_bf16 v[2:5], v[154:157], v[200:203], v[2:5]
	v_mfma_f32_16x16x32_bf16 v[50:53], v[150:153], v[166:169], v[50:53]
	v_mfma_f32_16x16x32_bf16 v[54:57], v[158:161], v[166:169], v[54:57]
	v_mfma_f32_16x16x32_bf16 v[34:37], v[150:153], v[188:191], v[34:37]
	v_mfma_f32_16x16x32_bf16 v[38:41], v[158:161], v[188:191], v[38:41]
	v_mfma_f32_16x16x32_bf16 v[18:21], v[150:153], v[196:199], v[18:21]
	v_mfma_f32_16x16x32_bf16 v[22:25], v[158:161], v[196:199], v[22:25]
	v_mfma_f32_16x16x32_bf16 v[6:9], v[150:153], v[214:217], v[6:9]
	v_mfma_f32_16x16x32_bf16 v[2:5], v[158:161], v[214:217], v[2:5]
	s_setprio 0
	s_barrier
	s_add_u32 s0, s0, 0x100
	s_addc_u32 s1, s1, 0
	s_add_u32 s42, s42, 0x100
	s_addc_u32 s43, s43, 0
	s_cmp_ge_u32 s44, s61
	s_mov_b32 s14, s44
	s_cbranch_scc1 .Lk_exit
